# R7_CA scaled-vector stage: row reads of the cumulative decay as 16/8-byte LDS reads (were 8-way bank-conflicting 4-byte reads); R7_FIN: norm vectors loaded once per phase, row pieces requested togethe
# speedup vs baseline: 1.0061x; 1.0061x over previous
; __device__ __forceinline__ float blo(unsigned u) { return __uint_as_float(u << 16); }
; __device__ __forceinline__ float bhi(unsigned u) { return __uint_as_float(u & 0xffff0000u); }
; __device__ __forceinline__ void ph_r7_ca(const P& p, int j, int win, char* smem) {
;     ...
;       const int tau = tid >> 3, sc = tid & 7, col = h * 64 + sc * 8; const int row = rowmap(d, b, 64 * c + tau);
;       const bfr* rp = RK + (size_t)row * 4096 + col; uint4 pr = *(const uint4*)rp, pk = *(const uint4*)(rp + 1024);
;       unsigned ur[4] = {pr.x, pr.y, pr.z, pr.w}, uk[4] = {pk.x, pk.y, pk.z, pk.w};
;       float r8[8], k8[8], kr[8];
; #pragma unroll
;       for (int e = 0; e < 4; e++) { r8[2 * e] = blo(ur[e]); r8[2 * e + 1] = bhi(ur[e]); k8[2 * e] = blo(uk[e]); k8[2 * e + 1] = bhi(uk[e]); }
;       float ss = 0.f;
; #pragma unroll
;       for (int e = 0; e < 8; e++) { kr[e] = k8[e] * kkp[col + e]; ss += kr[e] * kr[e]; }
;       ss += __shfl_xor(ss, 1); ss += __shfl_xor(ss, 2); ss += __shfl_xor(ss, 4);
;       const float inv = __builtin_amdgcn_rsqf(fmaxf(ss, 1e-24f));
;       float bon = 0.f, o0[8], o1[8], o2[8], o3[8], o4[8], o5[8];
; #pragma unroll
;       for (int e = 0; e < 8; e++) {
;         const float cw = LW[tau * 64 + sc * 8 + e], cwm = tau > 0 ? LW[(tau - 1) * 64 + sc * 8 + e] : 0.f, cwl = LW[63 * 64 + sc * 8 + e], a = AT[tau * 64 + sc * 8 + e];
;         const float ka = kr[e] * inv, be = a * ka, kd = k8[e] * (1.f + (a - 1.f) * kap[col + e]); bon += r8[e] * kd * rkp[col + e];
;         const float e2 = __expf(-cw), e4 = __expf(cwl - cw);
;         o0[e] = ka * __expf(cwm); o1[e] = be * e2; o2[e] = kd * e2; o3[e] = r8[e] * __expf(cw); o4[e] = be * e4; o5[e] = kd * e4;
;         if (tau == 63) WL[sc * 8 + e] = __expf(cwl);
;       }
;       bon += __shfl_xor(bon, 1); bon += __shfl_xor(bon, 2); bon += __shfl_xor(bon, 4);
;       if (sc == 0) BON[((size_t)d * R_ + row) * 16 + h] = bon;
.LBB0_190:
	s_or_b64 exec, exec, s[30:31]
	s_waitcnt lgkmcnt(0)
	s_barrier
	s_waitcnt vmcnt(0)
	v_lshlrev_b32_e32 v213, 16, v8
	v_and_b32_e32 v51, 0xffff0000, v8
	v_lshlrev_b32_e32 v49, 16, v9
	v_and_b32_e32 v48, 0xffff0000, v9
	v_lshlrev_b32_e32 v47, 16, v10
	v_and_b32_e32 v46, 0xffff0000, v10
	v_lshlrev_b32_e32 v45, 16, v11
	v_and_b32_e32 v43, 0xffff0000, v11
	v_mul_f32_e32 v28, v244, v47
	v_mul_f32_e32 v12, v15, v51
	v_mul_f32_e32 v14, v14, v213
	v_mul_f32_e32 v13, v12, v12
	v_fmac_f32_e32 v13, v14, v14
	v_mul_f32_e32 v22, v16, v49
	v_fmac_f32_e32 v13, v22, v22
	v_mul_f32_e32 v19, v17, v48
	v_fmac_f32_e32 v13, v19, v19
	v_fmac_f32_e32 v13, v28, v28
	v_mul_f32_e32 v25, v245, v46
	v_fmac_f32_e32 v13, v25, v25
	v_mul_f32_e32 v215, v246, v45
	v_fmac_f32_e32 v13, v215, v215
	v_mul_f32_e32 v50, v247, v43
	v_fmac_f32_e32 v13, v50, v50
	global_load_dword v226, v0, s[96:97]
	global_load_dword v225, v0, s[48:49]
	v_lshl_add_u64 v[178:179], s[96:97], 0, v[0:1]
	v_lshl_add_u64 v[10:11], s[48:49], 0, v[0:1]
	global_load_dword v229, v[178:179], off offset:4
	global_load_dword v228, v[10:11], off offset:4
	global_load_dword v233, v[178:179], off offset:8
	global_load_dword v231, v[10:11], off offset:8
	global_load_dword v235, v[178:179], off offset:12
	global_load_dword v234, v[10:11], off offset:12
	global_load_dword v240, v[178:179], off offset:16
	global_load_dword v239, v[10:11], off offset:16
	global_load_dword v243, v[178:179], off offset:20
	global_load_dword v242, v[10:11], off offset:20
	global_load_dword v245, v[178:179], off offset:24
	global_load_dword v244, v[10:11], off offset:24
	global_load_dword v247, v[178:179], off offset:28
	global_load_dword v246, v[10:11], off offset:28
	v_add_f32_dpp v8, v13, v13 quad_perm:[1,0,3,2] row_mask:0xf bank_mask:0xf
	s_nop 1
	v_add_f32_dpp v219, v8, v8 quad_perm:[2,3,0,1] row_mask:0xf bank_mask:0xf
	s_nop 1
	v_mov_b32_dpp v220, v219 row_half_mirror row_mask:0xf bank_mask:0xf
	ds_read_b128 v[8:11], v83 offset:64512
	ds_read_b64 v[58:59], v83 offset:64528
	ds_read_b64 v[64:65], v83 offset:64536
	ds_read_b32 v15, v84 offset:16128
	ds_read_b32 v0, v87 offset:16128
	ds_read_b32 v24, v90 offset:16128
	ds_read_b32 v30, v93 offset:16128
	ds_read_b32 v214, v96 offset:16128
	ds_read_b32 v221, v99 offset:16128
	ds_read_b32 v227, v102 offset:16128
	ds_read_b32 v237, v105 offset:16128
	ds_read_b32 v21, v85
	ds_read_b32 v20, v88
	ds_read_b32 v41, v91
	ds_read_b32 v31, v94
	ds_read_b32 v223, v97
	ds_read_b32 v222, v100
	ds_read_b32 v241, v103
	ds_read_b32 v238, v106
	s_waitcnt lgkmcnt(0)
	v_mov_b32_e32 v13, v8
	v_mov_b32_e32 v16, v9
	v_mov_b32_e32 v23, v10
	v_mov_b32_e32 v26, v11
	v_mov_b32_e32 v212, v58
	v_mov_b32_e32 v216, v59
	v_mov_b32_e32 v224, v64
	v_mov_b32_e32 v230, v65
	v_mov_b32_e32 v8, 0
	v_mov_b32_e32 v9, 0
	v_mov_b32_e32 v10, 0
	v_mov_b32_e32 v11, 0
	v_mov_b32_e32 v58, 0
	v_mov_b32_e32 v59, 0
	v_mov_b32_e32 v64, 0
	v_mov_b32_e32 v65, 0
	s_and_saveexec_b64 s[30:31], s[42:43]
	ds_read_b128 v[8:11], v60 offset:64256
	ds_read_b64 v[58:59], v60 offset:64272
	ds_read_b64 v[64:65], v60 offset:64280
	s_or_b64 exec, exec, s[30:31]
	s_and_saveexec_b64 s[30:31], s[44:45]
	s_cbranch_execz .LBB0_222
	v_mul_f32_e32 v178, 0x3fb8aa3b, v15
	v_mul_f32_e32 v179, 0x3fb8aa3b, v0
	v_mul_f32_e32 v57, 0x3fb8aa3b, v24
	v_mul_f32_e32 v66, 0x3fb8aa3b, v30
	v_exp_f32_e32 v178, v178
	v_exp_f32_e32 v179, v179
	v_exp_f32_e32 v57, v57
	v_exp_f32_e32 v66, v66
	s_nop 0
	ds_write_b32 v86, v178
	ds_write_b32 v89, v179
	ds_write_b32 v92, v57
	ds_write_b32 v95, v66
	v_mul_f32_e32 v178, 0x3fb8aa3b, v214
	v_mul_f32_e32 v179, 0x3fb8aa3b, v221
	v_mul_f32_e32 v57, 0x3fb8aa3b, v227
	v_mul_f32_e32 v66, 0x3fb8aa3b, v237
	v_exp_f32_e32 v178, v178
	v_exp_f32_e32 v179, v179
	v_exp_f32_e32 v57, v57
	v_exp_f32_e32 v66, v66
	s_nop 0
	ds_write_b32 v98, v178
	ds_write_b32 v101, v179
	ds_write_b32 v104, v57
	ds_write_b32 v107, v66
.LBB0_222:
	s_or_b64 exec, exec, s[30:31]
	s_waitcnt lgkmcnt(0)
	v_mul_f32_e32 v18, 0x3fb8aa3b, v8
	v_mul_f32_e32 v17, 0x3fb8aa3b, v9
	v_mul_f32_e32 v29, 0x3fb8aa3b, v10
	v_mul_f32_e32 v27, 0x3fb8aa3b, v11
	v_mul_f32_e32 v218, 0x3fb8aa3b, v58
	v_mul_f32_e32 v217, 0x3fb8aa3b, v59
	v_mul_f32_e32 v236, 0x3fb8aa3b, v64
	v_mul_f32_e32 v232, 0x3fb8aa3b, v65
	v_add_f32_e32 v8, -1.0, v21
	s_waitcnt vmcnt(15)
	v_fma_f32 v8, v8, v226, 1.0
	v_lshlrev_b32_e32 v11, 16, v2
	v_mul_f32_e32 v8, v8, v213
	v_mul_f32_e32 v9, v8, v11
	s_waitcnt vmcnt(14)
	v_fma_f32 v178, v225, v9, 0
	v_and_b32_e32 v9, 0xffff0000, v2
	v_add_f32_e32 v2, -1.0, v20
	s_waitcnt vmcnt(13)
	v_fma_f32 v2, v2, v229, 1.0
	v_mul_f32_e32 v10, v2, v51
	v_mul_f32_e32 v2, v10, v9
	s_waitcnt vmcnt(12)
	v_fmac_f32_e32 v178, v228, v2
	v_add_f32_e32 v2, -1.0, v41
	s_waitcnt vmcnt(11)
	v_fma_f32 v2, v2, v233, 1.0
	v_lshlrev_b32_e32 v51, 16, v3
	v_mul_f32_e32 v49, v2, v49
	v_mul_f32_e32 v2, v49, v51
	s_waitcnt vmcnt(10)
	v_fmac_f32_e32 v178, v231, v2
	s_waitcnt lgkmcnt(12)
	v_add_f32_e32 v2, -1.0, v31
	s_waitcnt vmcnt(9)
	v_fma_f32 v2, v2, v235, 1.0
	v_and_b32_e32 v3, 0xffff0000, v3
	v_mul_f32_e32 v48, v2, v48
	v_mul_f32_e32 v2, v48, v3
	s_waitcnt vmcnt(8)
	v_fmac_f32_e32 v178, v234, v2
	s_waitcnt lgkmcnt(9)
	v_add_f32_e32 v2, -1.0, v223
	s_waitcnt vmcnt(7)
	v_fma_f32 v2, v2, v240, 1.0
	v_lshlrev_b32_e32 v213, 16, v4
	v_mul_f32_e32 v47, v2, v47
	v_mul_f32_e32 v2, v47, v213
	s_waitcnt vmcnt(6)
	v_fmac_f32_e32 v178, v239, v2
	s_waitcnt lgkmcnt(6)
	v_add_f32_e32 v2, -1.0, v222
	s_waitcnt vmcnt(5)
	v_fma_f32 v2, v2, v243, 1.0
	v_and_b32_e32 v4, 0xffff0000, v4
	v_mul_f32_e32 v46, v2, v46
	v_mul_f32_e32 v2, v46, v4
	s_waitcnt vmcnt(4)
	v_fmac_f32_e32 v178, v242, v2
	s_waitcnt lgkmcnt(3)
	v_add_f32_e32 v2, -1.0, v241
	s_waitcnt vmcnt(3)
	v_fma_f32 v2, v2, v245, 1.0
	v_lshlrev_b32_e32 v225, 16, v5
	v_mul_f32_e32 v45, v2, v45
	v_mul_f32_e32 v2, v45, v225
	s_waitcnt vmcnt(2)
	v_fmac_f32_e32 v178, v244, v2
	s_waitcnt lgkmcnt(0)
	v_add_f32_e32 v2, -1.0, v238
	s_waitcnt vmcnt(1)
	v_fma_f32 v2, v2, v247, 1.0
	v_and_b32_e32 v5, 0xffff0000, v5
	v_mul_f32_e32 v43, v2, v43
	v_mul_f32_e32 v2, v43, v5
	s_waitcnt vmcnt(0)
	v_fmac_f32_e32 v178, v246, v2
	s_nop 1
	v_add_f32_dpp v2, v178, v178 quad_perm:[1,0,3,2] row_mask:0xf bank_mask:0xf
	s_nop 1
	v_add_f32_dpp v2, v2, v2 quad_perm:[2,3,0,1] row_mask:0xf bank_mask:0xf
	s_nop 1
	v_mov_b32_dpp v226, v2 row_half_mirror row_mask:0xf bank_mask:0xf
	s_and_saveexec_b64 s[30:31], s[46:47]
	s_cbranch_execz .LBB0_224
	s_mul_i32 s28, s86, 0x8200
	v_lshl_add_u64 v[6:7], v[6:7], 0, s[28:29]
	v_readlane_b32 s40, v251, 15
	v_lshlrev_b64 v[6:7], 6, v[6:7]
	v_readlane_b32 s41, v251, 16
	s_lshl_b32 s28, s85, 2
	v_add_f32_e32 v2, v2, v226
	v_lshl_add_u64 v[6:7], s[40:41], 0, v[6:7]
	v_lshl_add_u64 v[6:7], v[6:7], 0, s[28:29]
	global_store_dword v[6:7], v2, off
